# chunk-MLP unit prologue: param loads issued before the VG wait and second VG row prefetched early (merge independent round trips)
# baseline (speedup 1.0000x reference)
; __device__ __forceinline__ unsigned cvt_pk_bf16(float lo, float hi) { const f32x2 v = {lo, hi}; const bf16x2_t b = __builtin_convertvector(v, bf16x2_t); return __builtin_bit_cast(unsigned, b); }
; __device__ __forceinline__ void bmix_unit(LAS unsigned char* lds, const bf16_t* U, const bf16_t* VG, const float* gv  , const float* ws  , const float* bs  ,
;                                           int ci, int g, bf16_t* Y) {
;     ...
; #pragma unroll
;     for (int i = 0; i < 2; ++i) {
;         const int idx = tid + i * NTHREADS; const int q = idx >> 3, c8 = idx & 7;
;         const u32x4 w = *(const u32x4*)(VG + (size_t)(r0 + q) * 256 + g * 64 + c8 * 8); const float rs = rstd[q];
; #pragma unroll
;         for (int e = 0; e < 4; ++e) {
;             const float lo = __uint_as_float(w[e] << 16) * rs * gv[g * 64 + c8 * 8 + 2 * e], hi2 = __uint_as_float(w[e] & 0xffff0000u) * rs * gv[g * 64 + c8 * 8 + 2 * e + 1];
;             const unsigned pk = cvt_pk_bf16(lo, hi2);
;             vnT[(c8 * 8 + 2 * e) * 136 + q] = (bf16_t)(pk & 0xffffu); vnT[(c8 * 8 + 2 * e + 1) * 136 + q] = (bf16_t)(pk >> 16);
;         }
;     }
;     __syncthreads();
.LBB0_592:
	s_or_b64 exec, exec, s[0:1]
	s_and_b32 s0, s56, 3
	s_lshl_b32 s1, s0, 6
	s_lshl_b32 s0, s0, 7
	v_readlane_b32 s8, v254, 31
	v_lshlrev_b32_e32 v0, 3, v16
	v_ashrrev_i32_e32 v19, 3, v16
	v_readlane_b32 s9, v254, 32
	s_add_u32 s8, s8, s0
	v_and_b32_e32 v15, 56, v0
	v_add_u32_e32 v0, s6, v19
	s_addc_u32 s9, s9, 0
	v_lshlrev_b32_e32 v194, 1, v15
	s_waitcnt lgkmcnt(0)
	v_ashrrev_i32_e32 v1, 31, v0
	v_lshl_add_u64 v[12:13], s[8:9], 0, v[194:195]
	v_lshlrev_b64 v[0:1], 9, v[0:1]
	v_lshl_add_u64 v[0:1], v[12:13], 0, v[0:1]
	s_barrier
	global_load_dwordx4 v[8:11], v[0:1], off
	v_add_u32_e32 v24, 0x200, v16
	v_ashrrev_i32_e32 v24, 3, v24
	v_add_u32_e32 v24, s6, v24
	v_ashrrev_i32_e32 v25, 31, v24
	v_lshlrev_b64 v[24:25], 9, v[24:25]
	v_lshl_add_u64 v[24:25], v[12:13], 0, v[24:25]
	global_load_dword v24, v[24:25], off
	v_lshl_add_u32 v0, v19, 2, 0
	ds_read_b32 v14, v0
	v_or_b32_e32 v2, s1, v15
	v_lshlrev_b32_e32 v4, 2, v2
	s_movk_i32 s10, 0x110
	s_lshr_b32 s8, s7, 1
	global_load_dwordx4 v[0:3], v4, s[26:27] offset:16
	s_nop 0
	global_load_dwordx4 v[4:7], v4, s[26:27]
	s_and_b32 s8, s8, 0x60
	v_and_b32_e32 v17, 31, v16
	s_or_b32 s9, s0, s8
	v_readlane_b32 s12, v255, 27
	v_bfe_u32 v18, v16, 5, 1
	v_readlane_b32 s13, v255, 28
	s_waitcnt vmcnt(3)
	v_lshlrev_b32_e32 v22, 16, v8
	v_and_b32_e32 v23, 0xffff0000, v8
	s_waitcnt lgkmcnt(0)
	v_mul_f32_e32 v20, v14, v22
	v_mul_f32_e32 v21, v14, v23
	s_waitcnt vmcnt(0)
	v_mul_f32_e32 v20, v4, v20
	v_mul_f32_e32 v21, v5, v21
	s_nop 0
	v_cvt_pk_bf16_f32 v8, v20, v21
	v_mad_u32_u24 v20, v15, s10, 0
	v_lshl_add_u32 v15, v19, 1, v20
	ds_write_b16 v15, v8 offset:512
	ds_write_b16_d16_hi v15, v8 offset:784
	v_lshlrev_b32_e32 v8, 16, v9
	v_and_b32_e32 v9, 0xffff0000, v9
	v_mul_f32_e32 v8, v14, v8
	v_mul_f32_e32 v9, v14, v9
	v_mul_f32_e32 v8, v8, v6
	v_mul_f32_e32 v9, v9, v7
	s_nop 0
	v_cvt_pk_bf16_f32 v8, v8, v9
	ds_write_b16 v15, v8 offset:1056
	ds_write_b16_d16_hi v15, v8 offset:1328
	v_lshlrev_b32_e32 v8, 16, v10
	v_and_b32_e32 v9, 0xffff0000, v10
	v_mul_f32_e32 v8, v14, v8
	v_mul_f32_e32 v9, v14, v9
	v_mul_f32_e32 v8, v8, v0
	v_mul_f32_e32 v9, v9, v1
	s_nop 0
	v_cvt_pk_bf16_f32 v8, v8, v9
	ds_write_b16 v15, v8 offset:1600
	ds_write_b16_d16_hi v15, v8 offset:1872
	v_lshlrev_b32_e32 v8, 16, v11
	v_and_b32_e32 v9, 0xffff0000, v11
	v_mul_f32_e32 v8, v14, v8
	v_mul_f32_e32 v9, v14, v9
	v_mul_f32_e32 v8, v8, v2
	v_mul_f32_e32 v9, v9, v3
	s_nop 0
	v_cvt_pk_bf16_f32 v8, v8, v9
	ds_write_b16 v15, v8 offset:2144
	ds_write_b16_d16_hi v15, v8 offset:2416
	v_add_u32_e32 v8, 0x200, v16
	v_ashrrev_i32_e32 v19, 3, v8
	v_add_u32_e32 v8, s6, v19
	v_ashrrev_i32_e32 v9, 31, v8
	v_lshlrev_b64 v[8:9], 9, v[8:9]
	v_lshl_add_u64 v[8:9], v[12:13], 0, v[8:9]
	global_load_dwordx4 v[8:11], v[8:9], off
	v_lshl_add_u32 v12, v19, 2, 0
	ds_read_b32 v12, v12
	s_waitcnt vmcnt(0)
	v_lshlrev_b32_e32 v14, 16, v8
	v_and_b32_e32 v15, 0xffff0000, v8
	s_waitcnt lgkmcnt(0)
	v_mul_f32_e32 v14, v12, v14
	v_mul_f32_e32 v15, v12, v15
	v_mul_f32_e32 v4, v4, v14
	v_mul_f32_e32 v5, v5, v15
	v_lshl_add_u32 v8, v19, 1, v20
	v_cvt_pk_bf16_f32 v4, v4, v5
	ds_write_b16 v8, v4 offset:512
	ds_write_b16_d16_hi v8, v4 offset:784
	v_lshlrev_b32_e32 v4, 16, v9
	v_and_b32_e32 v5, 0xffff0000, v9
	v_mul_f32_e32 v4, v12, v4
	v_mul_f32_e32 v5, v12, v5
	v_mul_f32_e32 v4, v6, v4
	v_mul_f32_e32 v5, v7, v5
	s_nop 0
	v_cvt_pk_bf16_f32 v4, v4, v5
	ds_write_b16 v8, v4 offset:1056
	ds_write_b16_d16_hi v8, v4 offset:1328
	v_lshlrev_b32_e32 v4, 16, v10
	v_and_b32_e32 v5, 0xffff0000, v10
	v_mul_f32_e32 v4, v12, v4
	v_mul_f32_e32 v5, v12, v5
	v_mul_f32_e32 v0, v0, v4
	v_mul_f32_e32 v1, v1, v5
	s_nop 0
	v_cvt_pk_bf16_f32 v0, v0, v1
	ds_write_b16 v8, v0 offset:1600
	ds_write_b16_d16_hi v8, v0 offset:1872
	v_lshlrev_b32_e32 v0, 16, v11
	v_and_b32_e32 v1, 0xffff0000, v11
	v_mul_f32_e32 v0, v12, v0
	v_mul_f32_e32 v1, v12, v1
	v_mul_f32_e32 v0, v2, v0
	v_mul_f32_e32 v1, v3, v1
	s_nop 0
	v_cvt_pk_bf16_f32 v0, v0, v1
	ds_write_b16 v8, v0 offset:2144
	ds_write_b16_d16_hi v8, v0 offset:2416
	v_or_b32_e32 v0, s9, v17
	v_lshlrev_b32_e32 v194, 9, v0
	v_lshl_add_u64 v[0:1], s[12:13], 0, v[194:195]
	v_lshlrev_b32_e32 v194, 5, v18
	s_ashr_i32 s9, s7, 3
	v_lshl_add_u64 v[32:33], v[0:1], 0, v[194:195]
	s_and_b32 s7, s9, 0xffffffe0
	v_mov_b32_e32 v0, s9
	s_movk_i32 s9, 0xffe0
	v_bfi_b32 v0, s9, v0, v16
	v_mul_lo_u32 v0, v0, s10
	v_lshlrev_b32_e32 v1, 4, v18
	s_waitcnt lgkmcnt(0)
	s_barrier
; #define LAS __attribute__((address_space(3)))
; __device__ __forceinline__ unsigned cvt_pk_bf16(float lo, float hi) { const f32x2 v = {lo, hi}; const bf16x2_t b = __builtin_convertvector(v, bf16x2_t); return __builtin_bit_cast(unsigned, b); }
; __device__ __forceinline__ float bf2f(bf16_t v) { return __uint_as_float(((unsigned)v) << 16); }
; __device__ __forceinline__ int crow(int r, int hi) { return (r & 3) + 8 * (r >> 2) + 4 * hi; }
; __device__ __forceinline__ void bmix_unit(LAS unsigned char* lds, const bf16_t* U, const bf16_t* VG, const float* gv  , const float* ws  , const float* bs  ,
;                                           int ci, int g, bf16_t* Y) {
;     ...
;     const float* wrow = ws + ((size_t)g * 128 + pblk * 32 + r32) * 128 + hi * 8;
; #pragma unroll
;     for (int ks = 0; ks < 8; ++ks) {
;         const f32x4 a0 = *(const f32x4*)(wrow + ks * 16), a1 = *(const f32x4*)(wrow + ks * 16 + 4);
;         u32x4 aw; aw.x = cvt_pk_bf16(a0[0], a0[1]); aw.y = cvt_pk_bf16(a0[2], a0[3]); aw.z = cvt_pk_bf16(a1[0], a1[1]); aw.w = cvt_pk_bf16(a1[2], a1[3]);
;         const bf16x8 bfr = *(const LAS bf16x8*)(vnT + (cblk * 32 + r32) * 136 + ks * 16 + hi * 8);
;         acc = __builtin_amdgcn_mfma_f32_32x32x16_bf16(__builtin_bit_cast(bf16x8, aw), bfr, acc, 0, 0, 0);
;     }
; #pragma unroll
;     for (int r = 0; r < 16; ++r) {
;         const int p = pblk * 32 + crow(r, hi); const int col = g * 64 + cblk * 32 + r32;
;         const float mixed = acc[r] + bs[g * 128 + p];
;         const float uu = bf2f(U[(size_t)(r0 + p) * 256 + col]);
	v_add3_u32 v16, 0, v0, v1
	global_load_dwordx4 v[60:63], v[32:33], off
	global_load_dwordx4 v[64:67], v[32:33], off offset:16
	global_load_dwordx4 v[68:71], v[32:33], off offset:64
	global_load_dwordx4 v[72:75], v[32:33], off offset:80
	global_load_dwordx4 v[76:79], v[32:33], off offset:128
	global_load_dwordx4 v[80:83], v[32:33], off offset:144
	global_load_dwordx4 v[84:87], v[32:33], off offset:192
	global_load_dwordx4 v[88:91], v[32:33], off offset:208
	global_load_dwordx4 v[92:95], v[32:33], off offset:256
	global_load_dwordx4 v[96:99], v[32:33], off offset:272
	global_load_dwordx4 v[100:103], v[32:33], off offset:320
	global_load_dwordx4 v[104:107], v[32:33], off offset:336
	global_load_dwordx4 v[108:111], v[32:33], off offset:384
	global_load_dwordx4 v[112:115], v[32:33], off offset:400
	global_load_dwordx4 v[116:119], v[32:33], off offset:448
	global_load_dwordx4 v[120:123], v[32:33], off offset:464
	s_add_i32 s7, s7, s1
	ds_read_b128 v[124:127], v16 offset:512
	ds_read_b128 v[128:131], v16 offset:544
	ds_read_b128 v[132:135], v16 offset:576
	ds_read_b128 v[136:139], v16 offset:608
	ds_read_b128 v[140:143], v16 offset:640
	ds_read_b128 v[144:147], v16 offset:672
	ds_read_b128 v[148:151], v16 offset:704
	ds_read_b128 v[152:155], v16 offset:736
	v_or_b32_e32 v16, s7, v17
	s_waitcnt vmcnt(0) lgkmcnt(0)
	v_cvt_pk_bf16_f32 v156, v60, v61
	v_cvt_pk_bf16_f32 v157, v62, v63
	v_cvt_pk_bf16_f32 v158, v64, v65
	v_cvt_pk_bf16_f32 v159, v66, v67
	s_nop 1
	v_mfma_f32_32x32x16_bf16 v[0:15], v[156:159], v[124:127], 0
	v_cvt_pk_bf16_f32 v160, v68, v69
	v_cvt_pk_bf16_f32 v161, v70, v71
	v_cvt_pk_bf16_f32 v162, v72, v73
	v_cvt_pk_bf16_f32 v163, v74, v75
	s_nop 1
	v_mfma_f32_32x32x16_bf16 v[0:15], v[160:163], v[128:131], v[0:15]
	v_cvt_pk_bf16_f32 v156, v76, v77
	v_cvt_pk_bf16_f32 v157, v78, v79
	v_cvt_pk_bf16_f32 v158, v80, v81
	v_cvt_pk_bf16_f32 v159, v82, v83
	s_nop 1
	v_mfma_f32_32x32x16_bf16 v[0:15], v[156:159], v[132:135], v[0:15]
	v_cvt_pk_bf16_f32 v160, v84, v85
	v_cvt_pk_bf16_f32 v161, v86, v87
	v_cvt_pk_bf16_f32 v162, v88, v89
	v_cvt_pk_bf16_f32 v163, v90, v91
	s_nop 1
	v_mfma_f32_32x32x16_bf16 v[0:15], v[160:163], v[136:139], v[0:15]
	v_cvt_pk_bf16_f32 v156, v92, v93
	v_cvt_pk_bf16_f32 v157, v94, v95
	v_cvt_pk_bf16_f32 v158, v96, v97
	v_cvt_pk_bf16_f32 v159, v98, v99
	s_nop 1
	v_mfma_f32_32x32x16_bf16 v[0:15], v[156:159], v[140:143], v[0:15]
	v_cvt_pk_bf16_f32 v160, v100, v101
	v_cvt_pk_bf16_f32 v161, v102, v103
	v_cvt_pk_bf16_f32 v162, v104, v105
	v_cvt_pk_bf16_f32 v163, v106, v107
	s_nop 1
	v_mfma_f32_32x32x16_bf16 v[0:15], v[160:163], v[144:147], v[0:15]
	v_cvt_pk_bf16_f32 v156, v108, v109
	v_cvt_pk_bf16_f32 v157, v110, v111
	v_cvt_pk_bf16_f32 v158, v112, v113
	v_cvt_pk_bf16_f32 v159, v114, v115
	s_nop 1
	v_mfma_f32_32x32x16_bf16 v[0:15], v[156:159], v[148:151], v[0:15]
	v_cvt_pk_bf16_f32 v160, v116, v117
	v_cvt_pk_bf16_f32 v161, v118, v119
	v_cvt_pk_bf16_f32 v162, v120, v121
	v_cvt_pk_bf16_f32 v163, v122, v123
	s_nop 1
	v_mfma_f32_32x32x16_bf16 v[0:15], v[160:163], v[152:155], v[0:15]
	v_lshl_or_b32 v25, v18, 2, s8
	v_ashrrev_i32_e32 v17, 31, v16
	v_lshlrev_b64 v[20:21], 1, v[16:17]
	v_or_b32_e32 v16, s0, v25
	v_readlane_b32 s0, v255, 29
	v_lshlrev_b32_e32 v24, 2, v16
	v_readlane_b32 s1, v255, 30
	v_readlane_b32 s8, v254, 29
	v_readlane_b32 s9, v254, 30
	v_or_b32_e32 v194, s6, v25
	v_mov_b32_e32 v79, 0
	v_lshl_add_u64 v[22:23], s[8:9], 0, v[20:21]
	global_load_dwordx4 v[60:63], v24, s[0:1]
	global_load_dwordx4 v[64:67], v24, s[0:1] offset:32
	global_load_dwordx4 v[68:71], v24, s[0:1] offset:64
	global_load_dwordx4 v[72:75], v24, s[0:1] offset:96
	v_lshl_add_u64 v[76:77], s[86:87], 0, v[20:21]
	v_mov_b32_e32 v78, v194
	v_lshlrev_b64 v[80:81], 9, v[78:79]
	v_lshlrev_b64 v[82:83], 11, v[78:79]
	v_lshl_add_u64 v[80:81], v[22:23], 0, v[80:81]
	v_lshl_add_u64 v[100:101], v[76:77], 0, v[82:83]
	global_load_ushort v84, v[80:81], off
	v_or_b32_e32 v78, 1, v194
	v_lshlrev_b64 v[80:81], 9, v[78:79]
	v_lshlrev_b64 v[82:83], 11, v[78:79]
	v_lshl_add_u64 v[80:81], v[22:23], 0, v[80:81]
	v_lshl_add_u64 v[102:103], v[76:77], 0, v[82:83]
	global_load_ushort v85, v[80:81], off
	v_or_b32_e32 v78, 2, v194
	v_lshlrev_b64 v[80:81], 9, v[78:79]
	v_lshlrev_b64 v[82:83], 11, v[78:79]
	v_lshl_add_u64 v[80:81], v[22:23], 0, v[80:81]
	v_lshl_add_u64 v[104:105], v[76:77], 0, v[82:83]
	global_load_ushort v86, v[80:81], off
	v_or_b32_e32 v78, 3, v194
	v_lshlrev_b64 v[80:81], 9, v[78:79]
	v_lshlrev_b64 v[82:83], 11, v[78:79]
	v_lshl_add_u64 v[80:81], v[22:23], 0, v[80:81]
	v_lshl_add_u64 v[106:107], v[76:77], 0, v[82:83]
	global_load_ushort v87, v[80:81], off
	v_or_b32_e32 v78, 8, v194
	v_lshlrev_b64 v[80:81], 9, v[78:79]
	v_lshlrev_b64 v[82:83], 11, v[78:79]
	v_lshl_add_u64 v[80:81], v[22:23], 0, v[80:81]
	v_lshl_add_u64 v[108:109], v[76:77], 0, v[82:83]
	global_load_ushort v88, v[80:81], off
	v_or_b32_e32 v78, 9, v194
	v_lshlrev_b64 v[80:81], 9, v[78:79]
	v_lshlrev_b64 v[82:83], 11, v[78:79]
	v_lshl_add_u64 v[80:81], v[22:23], 0, v[80:81]
	v_lshl_add_u64 v[110:111], v[76:77], 0, v[82:83]
	global_load_ushort v89, v[80:81], off
	v_or_b32_e32 v78, 10, v194
	v_lshlrev_b64 v[80:81], 9, v[78:79]
	v_lshlrev_b64 v[82:83], 11, v[78:79]
	v_lshl_add_u64 v[80:81], v[22:23], 0, v[80:81]
; __device__ __forceinline__ unsigned cvt_pk_bf16(float lo, float hi) { const f32x2 v = {lo, hi}; const bf16x2_t b = __builtin_convertvector(v, bf16x2_t); return __builtin_bit_cast(unsigned, b); }
; __device__ __forceinline__ float bf2f(bf16_t v) { return __uint_as_float(((unsigned)v) << 16); }
; __device__ __forceinline__ int crow(int r, int hi) { return (r & 3) + 8 * (r >> 2) + 4 * hi; }
; __device__ __forceinline__ void bmix_unit(LAS unsigned char* lds, const bf16_t* U, const bf16_t* VG, const float* gv  , const float* ws  , const float* bs  ,
;                                           int ci, int g, bf16_t* Y) {
;     ...
; #pragma unroll
;     for (int r = 0; r < 16; ++r) {
;         const int p = pblk * 32 + crow(r, hi); const int col = g * 64 + cblk * 32 + r32;
;         const float mixed = acc[r] + bs[g * 128 + p];
;         const float uu = bf2f(U[(size_t)(r0 + p) * 256 + col]);
;         Y[(size_t)(r0 + p) * DM + 384 + col] = (bf16_t)(cvt_pk_bf16(uu * mixed, 0.f) & 0xffffu);
;     }
;     __syncthreads();
	v_lshl_add_u64 v[112:113], v[76:77], 0, v[82:83]
	global_load_ushort v90, v[80:81], off
	v_or_b32_e32 v78, 11, v194
	v_lshlrev_b64 v[80:81], 9, v[78:79]
	v_lshlrev_b64 v[82:83], 11, v[78:79]
	v_lshl_add_u64 v[80:81], v[22:23], 0, v[80:81]
	v_lshl_add_u64 v[114:115], v[76:77], 0, v[82:83]
	global_load_ushort v91, v[80:81], off
	v_or_b32_e32 v78, 16, v194
	v_lshlrev_b64 v[80:81], 9, v[78:79]
	v_lshlrev_b64 v[82:83], 11, v[78:79]
	v_lshl_add_u64 v[80:81], v[22:23], 0, v[80:81]
	v_lshl_add_u64 v[116:117], v[76:77], 0, v[82:83]
	global_load_ushort v92, v[80:81], off
	v_or_b32_e32 v78, 17, v194
	v_lshlrev_b64 v[80:81], 9, v[78:79]
	v_lshlrev_b64 v[82:83], 11, v[78:79]
	v_lshl_add_u64 v[80:81], v[22:23], 0, v[80:81]
	v_lshl_add_u64 v[118:119], v[76:77], 0, v[82:83]
	global_load_ushort v93, v[80:81], off
	v_or_b32_e32 v78, 18, v194
	v_lshlrev_b64 v[80:81], 9, v[78:79]
	v_lshlrev_b64 v[82:83], 11, v[78:79]
	v_lshl_add_u64 v[80:81], v[22:23], 0, v[80:81]
	v_lshl_add_u64 v[120:121], v[76:77], 0, v[82:83]
	global_load_ushort v94, v[80:81], off
	v_or_b32_e32 v78, 19, v194
	v_lshlrev_b64 v[80:81], 9, v[78:79]
	v_lshlrev_b64 v[82:83], 11, v[78:79]
	v_lshl_add_u64 v[80:81], v[22:23], 0, v[80:81]
	v_lshl_add_u64 v[122:123], v[76:77], 0, v[82:83]
	global_load_ushort v95, v[80:81], off
	v_or_b32_e32 v78, 24, v194
	v_lshlrev_b64 v[80:81], 9, v[78:79]
	v_lshlrev_b64 v[82:83], 11, v[78:79]
	v_lshl_add_u64 v[80:81], v[22:23], 0, v[80:81]
	v_lshl_add_u64 v[124:125], v[76:77], 0, v[82:83]
	global_load_ushort v96, v[80:81], off
	v_or_b32_e32 v78, 25, v194
	v_lshlrev_b64 v[80:81], 9, v[78:79]
	v_lshlrev_b64 v[82:83], 11, v[78:79]
	v_lshl_add_u64 v[80:81], v[22:23], 0, v[80:81]
	v_lshl_add_u64 v[126:127], v[76:77], 0, v[82:83]
	global_load_ushort v97, v[80:81], off
	v_or_b32_e32 v78, 26, v194
	v_lshlrev_b64 v[80:81], 9, v[78:79]
	v_lshlrev_b64 v[82:83], 11, v[78:79]
	v_lshl_add_u64 v[80:81], v[22:23], 0, v[80:81]
	v_lshl_add_u64 v[128:129], v[76:77], 0, v[82:83]
	global_load_ushort v98, v[80:81], off
	v_or_b32_e32 v78, 27, v194
	v_lshlrev_b64 v[80:81], 9, v[78:79]
	v_lshlrev_b64 v[82:83], 11, v[78:79]
	v_lshl_add_u64 v[80:81], v[22:23], 0, v[80:81]
	v_lshl_add_u64 v[130:131], v[76:77], 0, v[82:83]
	global_load_ushort v99, v[80:81], off
	s_waitcnt vmcnt(0)
	v_add_f32_e32 v132, v0, v60
	v_lshlrev_b32_e32 v84, 16, v84
	v_mul_f32_e32 v132, v132, v84
	v_cvt_pk_bf16_f32 v132, v132, v132
	global_store_short v[100:101], v132, off offset:768
	v_add_f32_e32 v133, v1, v61
	v_lshlrev_b32_e32 v85, 16, v85
	v_mul_f32_e32 v133, v133, v85
	v_cvt_pk_bf16_f32 v133, v133, v133
	global_store_short v[102:103], v133, off offset:768
	v_add_f32_e32 v134, v2, v62
	v_lshlrev_b32_e32 v86, 16, v86
	v_mul_f32_e32 v134, v134, v86
	v_cvt_pk_bf16_f32 v134, v134, v134
	global_store_short v[104:105], v134, off offset:768
	v_add_f32_e32 v135, v3, v63
	v_lshlrev_b32_e32 v87, 16, v87
	v_mul_f32_e32 v135, v135, v87
	v_cvt_pk_bf16_f32 v135, v135, v135
	global_store_short v[106:107], v135, off offset:768
	v_add_f32_e32 v136, v4, v64
	v_lshlrev_b32_e32 v88, 16, v88
	v_mul_f32_e32 v136, v136, v88
	v_cvt_pk_bf16_f32 v136, v136, v136
	global_store_short v[108:109], v136, off offset:768
	v_add_f32_e32 v137, v5, v65
	v_lshlrev_b32_e32 v89, 16, v89
	v_mul_f32_e32 v137, v137, v89
	v_cvt_pk_bf16_f32 v137, v137, v137
	global_store_short v[110:111], v137, off offset:768
	v_add_f32_e32 v138, v6, v66
	v_lshlrev_b32_e32 v90, 16, v90
	v_mul_f32_e32 v138, v138, v90
	v_cvt_pk_bf16_f32 v138, v138, v138
	global_store_short v[112:113], v138, off offset:768
	v_add_f32_e32 v139, v7, v67
	v_lshlrev_b32_e32 v91, 16, v91
	v_mul_f32_e32 v139, v139, v91
	v_cvt_pk_bf16_f32 v139, v139, v139
	global_store_short v[114:115], v139, off offset:768
	v_add_f32_e32 v140, v8, v68
	v_lshlrev_b32_e32 v92, 16, v92
	v_mul_f32_e32 v140, v140, v92
	v_cvt_pk_bf16_f32 v140, v140, v140
	global_store_short v[116:117], v140, off offset:768
	v_add_f32_e32 v141, v9, v69
	v_lshlrev_b32_e32 v93, 16, v93
	v_mul_f32_e32 v141, v141, v93
	v_cvt_pk_bf16_f32 v141, v141, v141
	global_store_short v[118:119], v141, off offset:768
	v_add_f32_e32 v142, v10, v70
	v_lshlrev_b32_e32 v94, 16, v94
	v_mul_f32_e32 v142, v142, v94
	v_cvt_pk_bf16_f32 v142, v142, v142
	global_store_short v[120:121], v142, off offset:768
	v_add_f32_e32 v143, v11, v71
	v_lshlrev_b32_e32 v95, 16, v95
	v_mul_f32_e32 v143, v143, v95
	v_cvt_pk_bf16_f32 v143, v143, v143
	global_store_short v[122:123], v143, off offset:768
	v_add_f32_e32 v144, v12, v72
	v_lshlrev_b32_e32 v96, 16, v96
	v_mul_f32_e32 v144, v144, v96
	v_cvt_pk_bf16_f32 v144, v144, v144
	global_store_short v[124:125], v144, off offset:768
	v_add_f32_e32 v145, v13, v73
	v_lshlrev_b32_e32 v97, 16, v97
	v_mul_f32_e32 v145, v145, v97
	v_cvt_pk_bf16_f32 v145, v145, v145
	global_store_short v[126:127], v145, off offset:768
	v_add_f32_e32 v146, v14, v74
	v_lshlrev_b32_e32 v98, 16, v98
	v_mul_f32_e32 v146, v146, v98
	v_cvt_pk_bf16_f32 v146, v146, v146
	global_store_short v[128:129], v146, off offset:768
	v_add_f32_e32 v147, v15, v75
	v_lshlrev_b32_e32 v99, 16, v99
	v_mul_f32_e32 v147, v147, v99
	v_cvt_pk_bf16_f32 v147, v147, v147
	global_store_short v[130:131], v147, off offset:768
	v_or_b32_e32 v194, 27, v194
	s_barrier
	s_mov_b64 s[0:1], 0
